# v57 + non-temporal hint on the P3 scan's KV loads only (read once); its SP stores keep the default policy
# speedup vs baseline: 1.0078x; 1.0078x over previous
; DI unsigned pk2(float lo, float hi) { f32x2 v = {lo, hi}; return __builtin_bit_cast(unsigned, __builtin_convertvector(v, bf16x2v)); }
; DI float bflo(unsigned u) { return __uint_as_float(u << 16); }
; DI float bfhi(unsigned u) { return __uint_as_float(u & 0xffff0000u); }
; DI void ret_scan(const bf16_t* KV, bf16_t* SP, float* o_state, int gt, int nthreads) {
;     for (int e = gt; e < 65536; e += nthreads) {
;         const int h = e >> 14, dv = (e >> 6) & 255, dk4 = (e & 63) * 4;
;         const float lg = log1pf(-exp2f(-5.0f - (float)h)), Dc = __expf(128.0f * lg), c1 = __expf(127.0f * lg);
;         const size_t base = ((size_t)(h * 256 + dv)) * 256 + dk4;
;         f32x4 s = {0.f, 0.f, 0.f, 0.f};
;         for (int n0 = 0; n0 < 64; n0 += 32) {
;             u32x2 q[32];
; #pragma unroll
;             for (int u = 0; u < 32; ++u) q[u] = *(const u32x2*)(KV + (size_t)(n0 + u) * 262144 + base);
; #pragma unroll
;             for (int u = 0; u < 32; ++u) { u32x2 o; o.x = pk2(s[0], s[1]); o.y = pk2(s[2], s[3]); *(u32x2*)(SP + (size_t)(n0 + u) * 262144 + base) = o;
;                 const f32x4 kv = {bflo(q[u].x), bfhi(q[u].x), bflo(q[u].y), bfhi(q[u].y)}; s = s * Dc + kv * c1; }
;         }
.LBB0_308:
	v_cndmask_b32_e64 v20, 0, 1, s[18:19]
	s_lshl_b64 s[6:7], s[16:17], 1
	v_cmp_ne_u32_e32 vcc, 1, v20
	v_lshl_add_u64 v[20:21], v[8:9], 0, s[6:7]
	global_load_dwordx2 v[82:83], v[20:21], off nt
	s_or_b32 s0, s16, 0x40000
	s_mov_b32 s1, s17
	s_lshl_b64 s[8:9], s[0:1], 1
	v_lshl_add_u64 v[20:21], v[8:9], 0, s[8:9]
	s_or_b32 s0, s16, 0x80000
	global_load_dwordx2 v[80:81], v[20:21], off nt
	s_lshl_b64 s[4:5], s[0:1], 1
	v_lshl_add_u64 v[20:21], v[8:9], 0, s[4:5]
	s_or_b32 s0, s16, 0xc0000
	global_load_dwordx2 v[78:79], v[20:21], off nt
	s_lshl_b64 s[12:13], s[0:1], 1
	v_lshl_add_u64 v[20:21], v[8:9], 0, s[12:13]
	s_or_b32 s0, s16, 0x100000
	global_load_dwordx2 v[76:77], v[20:21], off nt
	s_lshl_b64 s[0:1], s[0:1], 1
	v_lshl_add_u64 v[20:21], v[8:9], 0, s[0:1]
	s_or_b32 s18, s16, 0x140000
	s_mov_b32 s19, s17
	global_load_dwordx2 v[74:75], v[20:21], off nt
	s_lshl_b64 s[96:97], s[18:19], 1
	v_lshl_add_u64 v[20:21], v[8:9], 0, s[96:97]
	s_or_b32 s18, s16, 0x180000
	global_load_dwordx2 v[72:73], v[20:21], off nt
	s_lshl_b64 s[94:95], s[18:19], 1
	v_lshl_add_u64 v[20:21], v[8:9], 0, s[94:95]
	s_or_b32 s18, s16, 0x1c0000
	global_load_dwordx2 v[70:71], v[20:21], off nt
	s_lshl_b64 s[92:93], s[18:19], 1
	v_lshl_add_u64 v[20:21], v[8:9], 0, s[92:93]
	s_or_b32 s18, s16, 0x200000
	global_load_dwordx2 v[68:69], v[20:21], off nt
	s_lshl_b64 s[90:91], s[18:19], 1
	v_lshl_add_u64 v[20:21], v[8:9], 0, s[90:91]
	s_or_b32 s18, s16, 0x240000
	global_load_dwordx2 v[66:67], v[20:21], off nt
	s_lshl_b64 s[88:89], s[18:19], 1
	v_lshl_add_u64 v[20:21], v[8:9], 0, s[88:89]
	s_or_b32 s18, s16, 0x280000
	global_load_dwordx2 v[64:65], v[20:21], off nt
	s_lshl_b64 s[86:87], s[18:19], 1
	v_lshl_add_u64 v[20:21], v[8:9], 0, s[86:87]
	s_or_b32 s18, s16, 0x2c0000
	global_load_dwordx2 v[62:63], v[20:21], off nt
	s_lshl_b64 s[84:85], s[18:19], 1
	v_lshl_add_u64 v[20:21], v[8:9], 0, s[84:85]
	s_or_b32 s18, s16, 0x300000
	global_load_dwordx2 v[60:61], v[20:21], off nt
	s_lshl_b64 s[82:83], s[18:19], 1
	v_lshl_add_u64 v[20:21], v[8:9], 0, s[82:83]
	s_or_b32 s18, s16, 0x340000
	global_load_dwordx2 v[58:59], v[20:21], off nt
	s_lshl_b64 s[80:81], s[18:19], 1
	v_lshl_add_u64 v[20:21], v[8:9], 0, s[80:81]
	s_or_b32 s18, s16, 0x380000
	global_load_dwordx2 v[56:57], v[20:21], off nt
	s_lshl_b64 s[78:79], s[18:19], 1
	v_lshl_add_u64 v[20:21], v[8:9], 0, s[78:79]
	s_or_b32 s18, s16, 0x3c0000
	global_load_dwordx2 v[54:55], v[20:21], off nt
	s_lshl_b64 s[76:77], s[18:19], 1
	v_lshl_add_u64 v[20:21], v[8:9], 0, s[76:77]
	s_or_b32 s18, s16, 0x400000
	global_load_dwordx2 v[52:53], v[20:21], off nt
	s_lshl_b64 s[74:75], s[18:19], 1
	v_lshl_add_u64 v[20:21], v[8:9], 0, s[74:75]
	s_or_b32 s18, s16, 0x440000
	global_load_dwordx2 v[50:51], v[20:21], off nt
	s_lshl_b64 s[72:73], s[18:19], 1
	v_lshl_add_u64 v[20:21], v[8:9], 0, s[72:73]
	s_or_b32 s18, s16, 0x480000
	global_load_dwordx2 v[48:49], v[20:21], off nt
	s_lshl_b64 s[70:71], s[18:19], 1
	v_lshl_add_u64 v[20:21], v[8:9], 0, s[70:71]
	s_or_b32 s18, s16, 0x4c0000
	global_load_dwordx2 v[46:47], v[20:21], off nt
	s_lshl_b64 s[68:69], s[18:19], 1
	v_lshl_add_u64 v[20:21], v[8:9], 0, s[68:69]
	s_or_b32 s18, s16, 0x500000
	global_load_dwordx2 v[44:45], v[20:21], off nt
	s_lshl_b64 s[42:43], s[18:19], 1
	v_lshl_add_u64 v[20:21], v[8:9], 0, s[42:43]
	s_or_b32 s18, s16, 0x540000
	global_load_dwordx2 v[42:43], v[20:21], off nt
	s_lshl_b64 s[40:41], s[18:19], 1
	v_lshl_add_u64 v[20:21], v[8:9], 0, s[40:41]
	s_or_b32 s18, s16, 0x580000
	global_load_dwordx2 v[40:41], v[20:21], off nt
	s_lshl_b64 s[38:39], s[18:19], 1
	v_lshl_add_u64 v[20:21], v[8:9], 0, s[38:39]
	s_or_b32 s18, s16, 0x5c0000
	global_load_dwordx2 v[38:39], v[20:21], off nt
	s_lshl_b64 s[36:37], s[18:19], 1
	v_lshl_add_u64 v[20:21], v[8:9], 0, s[36:37]
	s_or_b32 s18, s16, 0x600000
	global_load_dwordx2 v[36:37], v[20:21], off nt
	s_lshl_b64 s[34:35], s[18:19], 1
	v_lshl_add_u64 v[20:21], v[8:9], 0, s[34:35]
	s_or_b32 s18, s16, 0x640000
	global_load_dwordx2 v[34:35], v[20:21], off nt
	s_lshl_b64 s[30:31], s[18:19], 1
	v_lshl_add_u64 v[20:21], v[8:9], 0, s[30:31]
	s_or_b32 s18, s16, 0x680000
	global_load_dwordx2 v[32:33], v[20:21], off nt
	s_lshl_b64 s[28:29], s[18:19], 1
	v_lshl_add_u64 v[20:21], v[8:9], 0, s[28:29]
	s_or_b32 s18, s16, 0x6c0000
	global_load_dwordx2 v[30:31], v[20:21], off nt
	v_cvt_pk_bf16_f32 v92, v18, v19
	v_cvt_pk_bf16_f32 v93, v16, v17
	v_lshl_add_u64 v[94:95], v[10:11], 0, s[6:7]
	s_lshl_b64 s[26:27], s[18:19], 1
	global_store_dwordx2 v[94:95], v[92:93], off
	s_waitcnt vmcnt(0)
; DI unsigned pk2(float lo, float hi) { f32x2 v = {lo, hi}; return __builtin_bit_cast(unsigned, __builtin_convertvector(v, bf16x2v)); }
; DI float bflo(unsigned u) { return __uint_as_float(u << 16); }
; DI float bfhi(unsigned u) { return __uint_as_float(u & 0xffff0000u); }
; DI void ret_scan(const bf16_t* KV, bf16_t* SP, float* o_state, int gt, int nthreads) {
;     ...
;         for (int n0 = 0; n0 < 64; n0 += 32) {
;             u32x2 q[32];
; #pragma unroll
;             for (int u = 0; u < 32; ++u) q[u] = *(const u32x2*)(KV + (size_t)(n0 + u) * 262144 + base);
; #pragma unroll
;             for (int u = 0; u < 32; ++u) { u32x2 o; o.x = pk2(s[0], s[1]); o.y = pk2(s[2], s[3]); *(u32x2*)(SP + (size_t)(n0 + u) * 262144 + base) = o;
;                 const f32x4 kv = {bflo(q[u].x), bfhi(q[u].x), bflo(q[u].y), bfhi(q[u].y)}; s = s * Dc + kv * c1; }
;         }
	v_lshlrev_b32_e32 v92, 16, v82
	v_and_b32_e32 v93, 0xffff0000, v82
	v_lshlrev_b32_e32 v82, 16, v83
	v_and_b32_e32 v83, 0xffff0000, v83
	v_lshl_add_u64 v[20:21], v[8:9], 0, s[26:27]
	v_pk_mul_f32 v[92:93], v[6:7], v[92:93]
	v_pk_mul_f32 v[82:83], v[14:15], v[82:83]
	s_or_b32 s18, s16, 0x700000
	global_load_dwordx2 v[28:29], v[20:21], off nt
	v_pk_fma_f32 v[16:17], v[12:13], v[16:17], v[82:83]
	v_pk_fma_f32 v[18:19], v[4:5], v[18:19], v[92:93]
	s_lshl_b64 s[24:25], s[18:19], 1
	v_cvt_pk_bf16_f32 v82, v18, v19
	v_cvt_pk_bf16_f32 v83, v16, v17
	v_lshl_add_u64 v[92:93], v[10:11], 0, s[8:9]
	v_lshl_add_u64 v[20:21], v[8:9], 0, s[24:25]
	global_store_dwordx2 v[92:93], v[82:83], off
	v_lshlrev_b32_e32 v82, 16, v80
	v_and_b32_e32 v83, 0xffff0000, v80
	v_lshlrev_b32_e32 v80, 16, v81
	v_and_b32_e32 v81, 0xffff0000, v81
	v_pk_mul_f32 v[18:19], v[4:5], v[18:19]
	v_pk_mul_f32 v[16:17], v[12:13], v[16:17]
	s_or_b32 s18, s16, 0x740000
	global_load_dwordx2 v[26:27], v[20:21], off nt
	v_pk_fma_f32 v[16:17], v[14:15], v[80:81], v[16:17]
	v_pk_fma_f32 v[18:19], v[6:7], v[82:83], v[18:19]
	s_lshl_b64 s[22:23], s[18:19], 1
	v_cvt_pk_bf16_f32 v80, v18, v19
	v_cvt_pk_bf16_f32 v81, v16, v17
	v_lshl_add_u64 v[82:83], v[10:11], 0, s[4:5]
	v_lshl_add_u64 v[20:21], v[8:9], 0, s[22:23]
	global_store_dwordx2 v[82:83], v[80:81], off
	v_lshlrev_b32_e32 v80, 16, v78
	v_and_b32_e32 v81, 0xffff0000, v78
	v_lshlrev_b32_e32 v78, 16, v79
	v_and_b32_e32 v79, 0xffff0000, v79
	v_pk_mul_f32 v[18:19], v[4:5], v[18:19]
	v_pk_mul_f32 v[16:17], v[12:13], v[16:17]
	s_or_b32 s18, s16, 0x780000
	global_load_dwordx2 v[24:25], v[20:21], off nt
	v_pk_fma_f32 v[16:17], v[14:15], v[78:79], v[16:17]
	v_pk_fma_f32 v[18:19], v[6:7], v[80:81], v[18:19]
	s_lshl_b64 s[20:21], s[18:19], 1
	v_cvt_pk_bf16_f32 v78, v18, v19
	v_cvt_pk_bf16_f32 v79, v16, v17
	v_lshl_add_u64 v[80:81], v[10:11], 0, s[12:13]
	v_lshl_add_u64 v[20:21], v[8:9], 0, s[20:21]
	global_store_dwordx2 v[80:81], v[78:79], off
	v_lshlrev_b32_e32 v78, 16, v76
	v_and_b32_e32 v79, 0xffff0000, v76
	v_lshlrev_b32_e32 v76, 16, v77
	v_and_b32_e32 v77, 0xffff0000, v77
	v_pk_mul_f32 v[18:19], v[4:5], v[18:19]
	v_pk_mul_f32 v[16:17], v[12:13], v[16:17]
	s_or_b32 s16, s16, 0x7c0000
	global_load_dwordx2 v[22:23], v[20:21], off nt
	v_pk_fma_f32 v[16:17], v[14:15], v[76:77], v[16:17]
	v_pk_fma_f32 v[18:19], v[6:7], v[78:79], v[18:19]
	s_lshl_b64 s[18:19], s[16:17], 1
	v_cvt_pk_bf16_f32 v76, v18, v19
	v_cvt_pk_bf16_f32 v77, v16, v17
	v_lshl_add_u64 v[78:79], v[10:11], 0, s[0:1]
	v_lshl_add_u64 v[20:21], v[8:9], 0, s[18:19]
	global_store_dwordx2 v[78:79], v[76:77], off
	v_lshlrev_b32_e32 v76, 16, v74
	v_and_b32_e32 v77, 0xffff0000, v74
	v_lshlrev_b32_e32 v74, 16, v75
	v_and_b32_e32 v75, 0xffff0000, v75
	v_pk_mul_f32 v[18:19], v[4:5], v[18:19]
	v_pk_mul_f32 v[16:17], v[12:13], v[16:17]
	global_load_dwordx2 v[20:21], v[20:21], off nt
	v_pk_fma_f32 v[16:17], v[14:15], v[74:75], v[16:17]
	v_pk_fma_f32 v[18:19], v[6:7], v[76:77], v[18:19]
	v_cvt_pk_bf16_f32 v75, v16, v17
	v_cvt_pk_bf16_f32 v74, v18, v19
	v_lshl_add_u64 v[76:77], v[10:11], 0, s[96:97]
	global_store_dwordx2 v[76:77], v[74:75], off
	v_lshlrev_b32_e32 v74, 16, v72
	v_and_b32_e32 v75, 0xffff0000, v72
	v_lshlrev_b32_e32 v72, 16, v73
	v_and_b32_e32 v73, 0xffff0000, v73
	v_pk_mul_f32 v[18:19], v[4:5], v[18:19]
	v_pk_mul_f32 v[16:17], v[12:13], v[16:17]
	v_pk_fma_f32 v[18:19], v[6:7], v[74:75], v[18:19]
	v_pk_fma_f32 v[16:17], v[14:15], v[72:73], v[16:17]
	v_cvt_pk_bf16_f32 v72, v18, v19
	v_cvt_pk_bf16_f32 v73, v16, v17
	v_lshl_add_u64 v[74:75], v[10:11], 0, s[94:95]
	global_store_dwordx2 v[74:75], v[72:73], off
	v_lshlrev_b32_e32 v72, 16, v70
	v_and_b32_e32 v73, 0xffff0000, v70
	v_lshlrev_b32_e32 v70, 16, v71
	v_and_b32_e32 v71, 0xffff0000, v71
	v_pk_mul_f32 v[18:19], v[4:5], v[18:19]
	v_pk_mul_f32 v[16:17], v[12:13], v[16:17]
	v_pk_fma_f32 v[18:19], v[6:7], v[72:73], v[18:19]
	v_pk_fma_f32 v[16:17], v[14:15], v[70:71], v[16:17]
	v_cvt_pk_bf16_f32 v70, v18, v19
	v_cvt_pk_bf16_f32 v71, v16, v17
	v_lshl_add_u64 v[72:73], v[10:11], 0, s[92:93]
	global_store_dwordx2 v[72:73], v[70:71], off
	v_lshlrev_b32_e32 v70, 16, v68
	v_and_b32_e32 v71, 0xffff0000, v68
	v_lshlrev_b32_e32 v68, 16, v69
	v_and_b32_e32 v69, 0xffff0000, v69
	v_pk_mul_f32 v[18:19], v[4:5], v[18:19]
	v_pk_mul_f32 v[16:17], v[12:13], v[16:17]
	v_pk_fma_f32 v[18:19], v[6:7], v[70:71], v[18:19]
	v_pk_fma_f32 v[16:17], v[14:15], v[68:69], v[16:17]
	v_cvt_pk_bf16_f32 v68, v18, v19
	v_cvt_pk_bf16_f32 v69, v16, v17
	v_lshl_add_u64 v[70:71], v[10:11], 0, s[90:91]
	global_store_dwordx2 v[70:71], v[68:69], off
	v_lshlrev_b32_e32 v68, 16, v66
	v_and_b32_e32 v69, 0xffff0000, v66
	v_lshlrev_b32_e32 v66, 16, v67
	v_and_b32_e32 v67, 0xffff0000, v67
	v_pk_mul_f32 v[18:19], v[4:5], v[18:19]
	v_pk_mul_f32 v[16:17], v[12:13], v[16:17]
	v_pk_fma_f32 v[18:19], v[6:7], v[68:69], v[18:19]
	v_pk_fma_f32 v[16:17], v[14:15], v[66:67], v[16:17]
	v_cvt_pk_bf16_f32 v66, v18, v19
	v_cvt_pk_bf16_f32 v67, v16, v17
	v_lshl_add_u64 v[68:69], v[10:11], 0, s[88:89]
	global_store_dwordx2 v[68:69], v[66:67], off
	v_lshlrev_b32_e32 v66, 16, v64
	v_and_b32_e32 v67, 0xffff0000, v64
	v_lshlrev_b32_e32 v64, 16, v65
	v_and_b32_e32 v65, 0xffff0000, v65
	v_pk_mul_f32 v[18:19], v[4:5], v[18:19]
	v_pk_mul_f32 v[16:17], v[12:13], v[16:17]
	v_pk_fma_f32 v[18:19], v[6:7], v[66:67], v[18:19]
	v_pk_fma_f32 v[16:17], v[14:15], v[64:65], v[16:17]
	v_cvt_pk_bf16_f32 v64, v18, v19
	v_cvt_pk_bf16_f32 v65, v16, v17
	v_lshl_add_u64 v[66:67], v[10:11], 0, s[86:87]
	global_store_dwordx2 v[66:67], v[64:65], off
	v_lshlrev_b32_e32 v64, 16, v62
	v_and_b32_e32 v65, 0xffff0000, v62
; DI unsigned pk2(float lo, float hi) { f32x2 v = {lo, hi}; return __builtin_bit_cast(unsigned, __builtin_convertvector(v, bf16x2v)); }
; DI float bflo(unsigned u) { return __uint_as_float(u << 16); }
; DI float bfhi(unsigned u) { return __uint_as_float(u & 0xffff0000u); }
; DI void ret_scan(const bf16_t* KV, bf16_t* SP, float* o_state, int gt, int nthreads) {
;     ...
;         for (int n0 = 0; n0 < 64; n0 += 32) {
;             u32x2 q[32];
; #pragma unroll
;             for (int u = 0; u < 32; ++u) q[u] = *(const u32x2*)(KV + (size_t)(n0 + u) * 262144 + base);
; #pragma unroll
;             for (int u = 0; u < 32; ++u) { u32x2 o; o.x = pk2(s[0], s[1]); o.y = pk2(s[2], s[3]); *(u32x2*)(SP + (size_t)(n0 + u) * 262144 + base) = o;
;                 const f32x4 kv = {bflo(q[u].x), bfhi(q[u].x), bflo(q[u].y), bfhi(q[u].y)}; s = s * Dc + kv * c1; }
;         }
	v_lshlrev_b32_e32 v62, 16, v63
	v_and_b32_e32 v63, 0xffff0000, v63
	v_pk_mul_f32 v[18:19], v[4:5], v[18:19]
	v_pk_mul_f32 v[16:17], v[12:13], v[16:17]
	v_pk_fma_f32 v[18:19], v[6:7], v[64:65], v[18:19]
	v_pk_fma_f32 v[16:17], v[14:15], v[62:63], v[16:17]
	v_cvt_pk_bf16_f32 v62, v18, v19
	v_cvt_pk_bf16_f32 v63, v16, v17
	v_lshl_add_u64 v[64:65], v[10:11], 0, s[84:85]
	global_store_dwordx2 v[64:65], v[62:63], off
	v_lshlrev_b32_e32 v62, 16, v60
	v_and_b32_e32 v63, 0xffff0000, v60
	v_lshlrev_b32_e32 v60, 16, v61
	v_and_b32_e32 v61, 0xffff0000, v61
	v_pk_mul_f32 v[18:19], v[4:5], v[18:19]
	v_pk_mul_f32 v[16:17], v[12:13], v[16:17]
	v_pk_fma_f32 v[18:19], v[6:7], v[62:63], v[18:19]
	v_pk_fma_f32 v[16:17], v[14:15], v[60:61], v[16:17]
	v_cvt_pk_bf16_f32 v60, v18, v19
	v_cvt_pk_bf16_f32 v61, v16, v17
	v_lshl_add_u64 v[62:63], v[10:11], 0, s[82:83]
	global_store_dwordx2 v[62:63], v[60:61], off
	v_lshlrev_b32_e32 v60, 16, v58
	v_and_b32_e32 v61, 0xffff0000, v58
	v_lshlrev_b32_e32 v58, 16, v59
	v_and_b32_e32 v59, 0xffff0000, v59
	v_pk_mul_f32 v[18:19], v[4:5], v[18:19]
	v_pk_mul_f32 v[16:17], v[12:13], v[16:17]
	v_pk_fma_f32 v[18:19], v[6:7], v[60:61], v[18:19]
	v_pk_fma_f32 v[16:17], v[14:15], v[58:59], v[16:17]
	v_cvt_pk_bf16_f32 v58, v18, v19
	v_cvt_pk_bf16_f32 v59, v16, v17
	v_lshl_add_u64 v[60:61], v[10:11], 0, s[80:81]
	global_store_dwordx2 v[60:61], v[58:59], off
	v_lshlrev_b32_e32 v58, 16, v56
	v_and_b32_e32 v59, 0xffff0000, v56
	v_lshlrev_b32_e32 v56, 16, v57
	v_and_b32_e32 v57, 0xffff0000, v57
	v_pk_mul_f32 v[18:19], v[4:5], v[18:19]
	v_pk_mul_f32 v[16:17], v[12:13], v[16:17]
	v_pk_fma_f32 v[18:19], v[6:7], v[58:59], v[18:19]
	v_pk_fma_f32 v[16:17], v[14:15], v[56:57], v[16:17]
	v_cvt_pk_bf16_f32 v56, v18, v19
	v_cvt_pk_bf16_f32 v57, v16, v17
	v_lshl_add_u64 v[58:59], v[10:11], 0, s[78:79]
	global_store_dwordx2 v[58:59], v[56:57], off
	v_lshlrev_b32_e32 v56, 16, v54
	v_and_b32_e32 v57, 0xffff0000, v54
	v_lshlrev_b32_e32 v54, 16, v55
	v_and_b32_e32 v55, 0xffff0000, v55
	v_pk_mul_f32 v[18:19], v[4:5], v[18:19]
	v_pk_mul_f32 v[16:17], v[12:13], v[16:17]
	v_pk_fma_f32 v[18:19], v[6:7], v[56:57], v[18:19]
	v_pk_fma_f32 v[16:17], v[14:15], v[54:55], v[16:17]
	v_cvt_pk_bf16_f32 v54, v18, v19
	v_cvt_pk_bf16_f32 v55, v16, v17
	v_lshl_add_u64 v[56:57], v[10:11], 0, s[76:77]
	global_store_dwordx2 v[56:57], v[54:55], off
	v_lshlrev_b32_e32 v54, 16, v52
	v_and_b32_e32 v55, 0xffff0000, v52
	v_lshlrev_b32_e32 v52, 16, v53
	v_and_b32_e32 v53, 0xffff0000, v53
	v_pk_mul_f32 v[18:19], v[4:5], v[18:19]
	v_pk_mul_f32 v[16:17], v[12:13], v[16:17]
	v_pk_fma_f32 v[18:19], v[6:7], v[54:55], v[18:19]
	v_pk_fma_f32 v[16:17], v[14:15], v[52:53], v[16:17]
	v_cvt_pk_bf16_f32 v52, v18, v19
	v_cvt_pk_bf16_f32 v53, v16, v17
	v_lshl_add_u64 v[54:55], v[10:11], 0, s[74:75]
	global_store_dwordx2 v[54:55], v[52:53], off
	v_lshlrev_b32_e32 v52, 16, v50
	v_and_b32_e32 v53, 0xffff0000, v50
	v_lshlrev_b32_e32 v50, 16, v51
	v_and_b32_e32 v51, 0xffff0000, v51
	v_pk_mul_f32 v[18:19], v[4:5], v[18:19]
	v_pk_mul_f32 v[16:17], v[12:13], v[16:17]
	v_pk_fma_f32 v[18:19], v[6:7], v[52:53], v[18:19]
	v_pk_fma_f32 v[16:17], v[14:15], v[50:51], v[16:17]
	v_cvt_pk_bf16_f32 v50, v18, v19
	v_cvt_pk_bf16_f32 v51, v16, v17
	v_lshl_add_u64 v[52:53], v[10:11], 0, s[72:73]
	global_store_dwordx2 v[52:53], v[50:51], off
	v_lshlrev_b32_e32 v50, 16, v48
	v_and_b32_e32 v51, 0xffff0000, v48
	v_lshlrev_b32_e32 v48, 16, v49
	v_and_b32_e32 v49, 0xffff0000, v49
	v_pk_mul_f32 v[18:19], v[4:5], v[18:19]
	v_pk_mul_f32 v[16:17], v[12:13], v[16:17]
	v_pk_fma_f32 v[18:19], v[6:7], v[50:51], v[18:19]
	v_pk_fma_f32 v[16:17], v[14:15], v[48:49], v[16:17]
	v_cvt_pk_bf16_f32 v48, v18, v19
	v_cvt_pk_bf16_f32 v49, v16, v17
	v_lshl_add_u64 v[50:51], v[10:11], 0, s[70:71]
	global_store_dwordx2 v[50:51], v[48:49], off
	v_lshlrev_b32_e32 v48, 16, v46
	v_and_b32_e32 v49, 0xffff0000, v46
	v_lshlrev_b32_e32 v46, 16, v47
	v_and_b32_e32 v47, 0xffff0000, v47
	v_pk_mul_f32 v[18:19], v[4:5], v[18:19]
	v_pk_mul_f32 v[16:17], v[12:13], v[16:17]
	v_pk_fma_f32 v[18:19], v[6:7], v[48:49], v[18:19]
	v_pk_fma_f32 v[16:17], v[14:15], v[46:47], v[16:17]
	v_cvt_pk_bf16_f32 v46, v18, v19
	v_cvt_pk_bf16_f32 v47, v16, v17
	v_lshl_add_u64 v[48:49], v[10:11], 0, s[68:69]
	global_store_dwordx2 v[48:49], v[46:47], off
	v_lshlrev_b32_e32 v46, 16, v44
	v_and_b32_e32 v47, 0xffff0000, v44
	v_lshlrev_b32_e32 v44, 16, v45
	v_and_b32_e32 v45, 0xffff0000, v45
	v_pk_mul_f32 v[18:19], v[4:5], v[18:19]
	v_pk_mul_f32 v[16:17], v[12:13], v[16:17]
	v_pk_fma_f32 v[18:19], v[6:7], v[46:47], v[18:19]
	v_pk_fma_f32 v[16:17], v[14:15], v[44:45], v[16:17]
	v_cvt_pk_bf16_f32 v44, v18, v19
	v_cvt_pk_bf16_f32 v45, v16, v17
	v_lshl_add_u64 v[46:47], v[10:11], 0, s[42:43]
	global_store_dwordx2 v[46:47], v[44:45], off
	v_lshlrev_b32_e32 v44, 16, v42
	v_and_b32_e32 v45, 0xffff0000, v42
	v_lshlrev_b32_e32 v42, 16, v43
	v_and_b32_e32 v43, 0xffff0000, v43
	v_pk_mul_f32 v[18:19], v[4:5], v[18:19]
	v_pk_mul_f32 v[16:17], v[12:13], v[16:17]
	v_pk_fma_f32 v[18:19], v[6:7], v[44:45], v[18:19]
	v_pk_fma_f32 v[16:17], v[14:15], v[42:43], v[16:17]
	v_cvt_pk_bf16_f32 v42, v18, v19
	v_cvt_pk_bf16_f32 v43, v16, v17
	v_lshl_add_u64 v[44:45], v[10:11], 0, s[40:41]
	global_store_dwordx2 v[44:45], v[42:43], off
	v_lshlrev_b32_e32 v42, 16, v40
	v_and_b32_e32 v43, 0xffff0000, v40
	v_lshlrev_b32_e32 v40, 16, v41
	v_and_b32_e32 v41, 0xffff0000, v41
	v_pk_mul_f32 v[18:19], v[4:5], v[18:19]
	v_pk_mul_f32 v[16:17], v[12:13], v[16:17]
	v_pk_fma_f32 v[18:19], v[6:7], v[42:43], v[18:19]
	v_pk_fma_f32 v[16:17], v[14:15], v[40:41], v[16:17]
	v_cvt_pk_bf16_f32 v40, v18, v19
	v_cvt_pk_bf16_f32 v41, v16, v17
; DI unsigned pk2(float lo, float hi) { f32x2 v = {lo, hi}; return __builtin_bit_cast(unsigned, __builtin_convertvector(v, bf16x2v)); }
; DI float bflo(unsigned u) { return __uint_as_float(u << 16); }
; DI float bfhi(unsigned u) { return __uint_as_float(u & 0xffff0000u); }
; DI void ret_scan(const bf16_t* KV, bf16_t* SP, float* o_state, int gt, int nthreads) {
;     ...
;         for (int n0 = 0; n0 < 64; n0 += 32) {
;             u32x2 q[32];
; #pragma unroll
;             for (int u = 0; u < 32; ++u) q[u] = *(const u32x2*)(KV + (size_t)(n0 + u) * 262144 + base);
; #pragma unroll
;             for (int u = 0; u < 32; ++u) { u32x2 o; o.x = pk2(s[0], s[1]); o.y = pk2(s[2], s[3]); *(u32x2*)(SP + (size_t)(n0 + u) * 262144 + base) = o;
;                 const f32x4 kv = {bflo(q[u].x), bfhi(q[u].x), bflo(q[u].y), bfhi(q[u].y)}; s = s * Dc + kv * c1; }
;         }
; #pragma unroll
;         for (int j = 0; j < 4; ++j) o_state[((size_t)(h * 256 + dk4 + j)) * 256 + dv] = s[j];
;     }
	v_lshl_add_u64 v[42:43], v[10:11], 0, s[38:39]
	global_store_dwordx2 v[42:43], v[40:41], off
	v_lshlrev_b32_e32 v40, 16, v38
	v_and_b32_e32 v41, 0xffff0000, v38
	v_lshlrev_b32_e32 v38, 16, v39
	v_and_b32_e32 v39, 0xffff0000, v39
	v_pk_mul_f32 v[18:19], v[4:5], v[18:19]
	v_pk_mul_f32 v[16:17], v[12:13], v[16:17]
	v_pk_fma_f32 v[18:19], v[6:7], v[40:41], v[18:19]
	v_pk_fma_f32 v[16:17], v[14:15], v[38:39], v[16:17]
	v_cvt_pk_bf16_f32 v38, v18, v19
	v_cvt_pk_bf16_f32 v39, v16, v17
	v_lshl_add_u64 v[40:41], v[10:11], 0, s[36:37]
	global_store_dwordx2 v[40:41], v[38:39], off
	v_lshlrev_b32_e32 v38, 16, v36
	v_and_b32_e32 v39, 0xffff0000, v36
	v_lshlrev_b32_e32 v36, 16, v37
	v_and_b32_e32 v37, 0xffff0000, v37
	v_pk_mul_f32 v[18:19], v[4:5], v[18:19]
	v_pk_mul_f32 v[16:17], v[12:13], v[16:17]
	v_pk_fma_f32 v[18:19], v[6:7], v[38:39], v[18:19]
	v_pk_fma_f32 v[16:17], v[14:15], v[36:37], v[16:17]
	v_cvt_pk_bf16_f32 v36, v18, v19
	v_cvt_pk_bf16_f32 v37, v16, v17
	v_lshl_add_u64 v[38:39], v[10:11], 0, s[34:35]
	global_store_dwordx2 v[38:39], v[36:37], off
	v_lshlrev_b32_e32 v36, 16, v34
	v_and_b32_e32 v37, 0xffff0000, v34
	v_lshlrev_b32_e32 v34, 16, v35
	v_and_b32_e32 v35, 0xffff0000, v35
	v_pk_mul_f32 v[18:19], v[4:5], v[18:19]
	v_pk_mul_f32 v[16:17], v[12:13], v[16:17]
	v_pk_fma_f32 v[18:19], v[6:7], v[36:37], v[18:19]
	v_pk_fma_f32 v[16:17], v[14:15], v[34:35], v[16:17]
	v_cvt_pk_bf16_f32 v34, v18, v19
	v_cvt_pk_bf16_f32 v35, v16, v17
	v_lshl_add_u64 v[36:37], v[10:11], 0, s[30:31]
	global_store_dwordx2 v[36:37], v[34:35], off
	v_lshlrev_b32_e32 v34, 16, v32
	v_and_b32_e32 v35, 0xffff0000, v32
	v_lshlrev_b32_e32 v32, 16, v33
	v_and_b32_e32 v33, 0xffff0000, v33
	v_pk_mul_f32 v[18:19], v[4:5], v[18:19]
	v_pk_mul_f32 v[16:17], v[12:13], v[16:17]
	v_pk_fma_f32 v[18:19], v[6:7], v[34:35], v[18:19]
	v_pk_fma_f32 v[16:17], v[14:15], v[32:33], v[16:17]
	v_cvt_pk_bf16_f32 v32, v18, v19
	v_cvt_pk_bf16_f32 v33, v16, v17
	v_lshl_add_u64 v[34:35], v[10:11], 0, s[28:29]
	global_store_dwordx2 v[34:35], v[32:33], off
	v_lshlrev_b32_e32 v32, 16, v30
	v_and_b32_e32 v33, 0xffff0000, v30
	v_lshlrev_b32_e32 v30, 16, v31
	v_and_b32_e32 v31, 0xffff0000, v31
	v_pk_mul_f32 v[18:19], v[4:5], v[18:19]
	v_pk_mul_f32 v[16:17], v[12:13], v[16:17]
	v_pk_fma_f32 v[18:19], v[6:7], v[32:33], v[18:19]
	v_pk_fma_f32 v[16:17], v[14:15], v[30:31], v[16:17]
	v_cvt_pk_bf16_f32 v30, v18, v19
	v_cvt_pk_bf16_f32 v31, v16, v17
	v_lshl_add_u64 v[32:33], v[10:11], 0, s[26:27]
	global_store_dwordx2 v[32:33], v[30:31], off
	s_waitcnt vmcnt(31)
	v_lshlrev_b32_e32 v30, 16, v28
	v_and_b32_e32 v31, 0xffff0000, v28
	v_lshlrev_b32_e32 v28, 16, v29
	v_and_b32_e32 v29, 0xffff0000, v29
	v_pk_mul_f32 v[18:19], v[4:5], v[18:19]
	v_pk_mul_f32 v[16:17], v[12:13], v[16:17]
	v_pk_fma_f32 v[18:19], v[6:7], v[30:31], v[18:19]
	v_pk_fma_f32 v[16:17], v[14:15], v[28:29], v[16:17]
	v_cvt_pk_bf16_f32 v28, v18, v19
	v_cvt_pk_bf16_f32 v29, v16, v17
	v_lshl_add_u64 v[30:31], v[10:11], 0, s[24:25]
	global_store_dwordx2 v[30:31], v[28:29], off
	s_waitcnt vmcnt(30)
	v_lshlrev_b32_e32 v28, 16, v26
	v_and_b32_e32 v29, 0xffff0000, v26
	v_lshlrev_b32_e32 v26, 16, v27
	v_and_b32_e32 v27, 0xffff0000, v27
	v_pk_mul_f32 v[18:19], v[4:5], v[18:19]
	v_pk_mul_f32 v[16:17], v[12:13], v[16:17]
	v_pk_fma_f32 v[18:19], v[6:7], v[28:29], v[18:19]
	v_pk_fma_f32 v[16:17], v[14:15], v[26:27], v[16:17]
	v_cvt_pk_bf16_f32 v26, v18, v19
	v_cvt_pk_bf16_f32 v27, v16, v17
	v_lshl_add_u64 v[28:29], v[10:11], 0, s[22:23]
	global_store_dwordx2 v[28:29], v[26:27], off
	s_waitcnt vmcnt(29)
	v_lshlrev_b32_e32 v26, 16, v24
	v_and_b32_e32 v27, 0xffff0000, v24
	v_lshlrev_b32_e32 v24, 16, v25
	v_and_b32_e32 v25, 0xffff0000, v25
	v_pk_mul_f32 v[18:19], v[4:5], v[18:19]
	v_pk_mul_f32 v[16:17], v[12:13], v[16:17]
	v_pk_fma_f32 v[18:19], v[6:7], v[26:27], v[18:19]
	v_pk_fma_f32 v[16:17], v[14:15], v[24:25], v[16:17]
	v_cvt_pk_bf16_f32 v24, v18, v19
	v_cvt_pk_bf16_f32 v25, v16, v17
	v_lshl_add_u64 v[26:27], v[10:11], 0, s[20:21]
	global_store_dwordx2 v[26:27], v[24:25], off
	s_waitcnt vmcnt(28)
	v_lshlrev_b32_e32 v24, 16, v22
	v_and_b32_e32 v25, 0xffff0000, v22
	v_lshlrev_b32_e32 v22, 16, v23
	v_and_b32_e32 v23, 0xffff0000, v23
	v_pk_mul_f32 v[18:19], v[4:5], v[18:19]
	v_pk_mul_f32 v[16:17], v[12:13], v[16:17]
	v_pk_fma_f32 v[18:19], v[6:7], v[24:25], v[18:19]
	v_pk_fma_f32 v[16:17], v[14:15], v[22:23], v[16:17]
	v_cvt_pk_bf16_f32 v22, v18, v19
	v_cvt_pk_bf16_f32 v23, v16, v17
	v_lshl_add_u64 v[24:25], v[10:11], 0, s[18:19]
	global_store_dwordx2 v[24:25], v[22:23], off
	s_waitcnt vmcnt(27)
	v_lshlrev_b32_e32 v22, 16, v20
	v_and_b32_e32 v23, 0xffff0000, v20
	v_lshlrev_b32_e32 v20, 16, v21
	v_and_b32_e32 v21, 0xffff0000, v21
	v_pk_mul_f32 v[18:19], v[4:5], v[18:19]
	v_pk_mul_f32 v[16:17], v[12:13], v[16:17]
	v_pk_fma_f32 v[18:19], v[6:7], v[22:23], v[18:19]
	v_pk_fma_f32 v[16:17], v[14:15], v[20:21], v[16:17]
	s_mov_b32 s16, 0x800000
	s_mov_b64 s[18:19], 0
	s_cbranch_vccz .LBB0_308
	v_or_b32_e32 v4, v3, v90
	v_lshlrev_b32_e32 v0, 2, v0
	v_ashrrev_i32_e32 v5, 31, v4
	v_lshl_add_u64 v[6:7], s[10:11], 0, v[0:1]
	v_lshlrev_b64 v[8:9], 10, v[4:5]
	v_lshl_add_u64 v[8:9], v[6:7], 0, v[8:9]
	global_store_dword v[8:9], v18, off
	v_or_b32_e32 v8, 1, v4
	v_ashrrev_i32_e32 v9, 31, v8
	v_lshlrev_b64 v[8:9], 10, v[8:9]
	v_lshl_add_u64 v[8:9], v[6:7], 0, v[8:9]
	global_store_dword v[8:9], v19, off
	v_or_b32_e32 v8, 2, v4
	v_or_b32_e32 v4, 3, v4
	v_ashrrev_i32_e32 v9, 31, v8
	v_ashrrev_i32_e32 v5, 31, v4
	v_add_u32_e32 v84, s33, v84
	s_mov_b32 s0, 0xffff
	v_lshlrev_b64 v[8:9], 10, v[8:9]
	v_lshlrev_b64 v[4:5], 10, v[4:5]
	v_cmp_lt_i32_e32 vcc, s0, v84
	v_lshl_add_u64 v[8:9], v[6:7], 0, v[8:9]
	v_lshl_add_u64 v[4:5], v[6:7], 0, v[4:5]
	s_or_b64 s[14:15], vcc, s[14:15]
	global_store_dword v[8:9], v16, off
	global_store_dword v[4:5], v17, off
	s_andn2_b64 exec, exec, s[14:15]
	s_cbranch_execnz .LBB0_307
